# gate GEMM sigmoid epilogue hand-written with packed f32 ops (same per-element order), two register pairs interleaved, 32-bit saddr store offsets
# baseline (speedup 1.0000x reference)
; __device__ __forceinline__ float sigmoidf_(float x) { return __builtin_amdgcn_rcpf(1.f + __expf(-x)); }
; #define WIDE_STORE(BASE, LD, COFF, O) do { if ((m & 1) == 0) opend[n] = (O); \
;                 else *(uint4*)((BASE) + (size_t)tok * (LD) + (ncw - (COFF))) = swap_pair(opend[n], (O)); } while (0)
;     ...
;       uint2 opend[2];
; #pragma unroll
;       for (int ai = 0; ai < 2; ++ai)
; #pragma unroll
;         for (int bj = 0; bj < 2; ++bj)
; #pragma unroll
;           for (int m = 0; m < 4; ++m)
; #pragma unroll
;             for (int n = 0; n < 2; ++n) {
;               const int nc = brow + ai * 128 + wr * 64 + m * 16 + fq * 4;
;               const int tok = bcol + bj * 128 + wc * 32 + n * 16 + fr;
;               const int ncw = brow + ai * 128 + wr * 64 + ((m & ~1) + (fq & 1)) * 16 + (fq & ~1) * 4;
;     ...
;               f32x4 v = acc[ai][bj][m][n];
;               if (MODE == 0) {
;                 if (tn == 52) {
;                   if (ai == 0) *(float4*)((float*)(ws + OFF_DTR) + (size_t)tok * 128 + (nc - 13312)) = make_float4(v[0], v[1], v[2], v[3]);
;                 } else {
;                   u16* dst; int ld, c0;
;                   if (tn < 16) { dst = (u16*)(ws + OFF_Z); ld = 4096; c0 = 0; }
;                   else if (tn < 40) { dst = (u16*)(ws + OFF_RA); ld = 6144; c0 = 4096; }
;                   else if (tn < 48) { dst = (u16*)(ws + OFF_Q); ld = 2048; c0 = 10240; }
;                   else if (tn < 50) { dst = (u16*)(ws + OFF_K); ld = 512; c0 = 12288; }
;                   else { dst = (u16*)(ws + OFF_V); ld = 512; c0 = 12800; }
;                   uint2 o; o.x = pk2(v[0], v[1]); o.y = pk2(v[2], v[3]);
;                   WIDE_STORE(dst, ld, c0, o);
;                 }
;               } else if (MODE == 1) {
;                 uint2 o; o.x = pk2(sigmoidf_(v[0]), sigmoidf_(v[1])); o.y = pk2(sigmoidf_(v[2]), sigmoidf_(v[3]));
;                 WIDE_STORE((u16*)outp, 4096, 0, o);
.LBB0_553:
	v_mov_b32_e32 v250, 0xbfb8aa3b
	v_mov_b32_e32 v252, 1.0
	s_or_b32 s1, s0, s54
	v_and_b32_e32 v128, 63, v138
	v_and_or_b32 v129, v128, 15, s1
	v_readlane_b32 s1, v246, 52
	v_ashrrev_i32_e32 v130, 2, v128
	v_and_b32_e32 v130, -8, v130
	v_and_b32_e32 v131, 16, v128
	s_add_i32 s1, s2, s1
	v_add3_u32 v130, v130, v131, s1
	v_lshlrev_b32_e32 v130, 1, v130
	v_lshl_add_u32 v247, v129, 13, v130
	v_add_u32_e32 v248, 0x20000, v247
	v_add_u32_e32 v249, 0x100000, v247
	v_add_u32_e32 v254, 0x120000, v247
	v_readlane_b32 s0, v243, 57
	v_readlane_b32 s1, v243, 58
	v_pk_mul_f32 v[132:133], v[124:125], v[250:251] op_sel_hi:[1,0]
	v_pk_mul_f32 v[134:135], v[126:127], v[250:251] op_sel_hi:[1,0]
	v_exp_f32_e32 v132, v132
	v_exp_f32_e32 v133, v133
	v_exp_f32_e32 v134, v134
	v_exp_f32_e32 v135, v135
	v_pk_add_f32 v[132:133], v[132:133], v[252:253] op_sel_hi:[1,0]
	v_pk_add_f32 v[134:135], v[134:135], v[252:253] op_sel_hi:[1,0]
	v_rcp_f32_e32 v132, v132
	v_rcp_f32_e32 v133, v133
	v_rcp_f32_e32 v134, v134
	v_rcp_f32_e32 v135, v135
	v_cvt_pk_bf16_f32 v124, v132, v133
	v_cvt_pk_bf16_f32 v125, v134, v135
	v_pk_mul_f32 v[132:133], v[116:117], v[250:251] op_sel_hi:[1,0]
	v_pk_mul_f32 v[134:135], v[118:119], v[250:251] op_sel_hi:[1,0]
	v_exp_f32_e32 v132, v132
	v_exp_f32_e32 v133, v133
	v_exp_f32_e32 v134, v134
	v_exp_f32_e32 v135, v135
	v_pk_add_f32 v[132:133], v[132:133], v[252:253] op_sel_hi:[1,0]
	v_pk_add_f32 v[134:135], v[134:135], v[252:253] op_sel_hi:[1,0]
	v_rcp_f32_e32 v132, v132
	v_rcp_f32_e32 v133, v133
	v_rcp_f32_e32 v134, v134
	v_rcp_f32_e32 v135, v135
	v_cvt_pk_bf16_f32 v126, v132, v133
	v_cvt_pk_bf16_f32 v127, v134, v135
	s_nop 1
	v_permlane16_swap_b32_e32 v124, v126
	v_permlane16_swap_b32_e32 v125, v127
	global_store_dwordx4 v247, v[124:127], s[0:1]
	v_pk_mul_f32 v[132:133], v[120:121], v[250:251] op_sel_hi:[1,0]
	v_pk_mul_f32 v[134:135], v[122:123], v[250:251] op_sel_hi:[1,0]
	v_exp_f32_e32 v132, v132
	v_exp_f32_e32 v133, v133
	v_exp_f32_e32 v134, v134
	v_exp_f32_e32 v135, v135
	v_pk_add_f32 v[132:133], v[132:133], v[252:253] op_sel_hi:[1,0]
	v_pk_add_f32 v[134:135], v[134:135], v[252:253] op_sel_hi:[1,0]
	v_rcp_f32_e32 v132, v132
	v_rcp_f32_e32 v133, v133
	v_rcp_f32_e32 v134, v134
	v_rcp_f32_e32 v135, v135
	v_cvt_pk_bf16_f32 v120, v132, v133
	v_cvt_pk_bf16_f32 v121, v134, v135
	v_pk_mul_f32 v[132:133], v[112:113], v[250:251] op_sel_hi:[1,0]
	v_pk_mul_f32 v[134:135], v[114:115], v[250:251] op_sel_hi:[1,0]
	v_exp_f32_e32 v132, v132
	v_exp_f32_e32 v133, v133
	v_exp_f32_e32 v134, v134
	v_exp_f32_e32 v135, v135
	v_pk_add_f32 v[132:133], v[132:133], v[252:253] op_sel_hi:[1,0]
	v_pk_add_f32 v[134:135], v[134:135], v[252:253] op_sel_hi:[1,0]
	v_rcp_f32_e32 v132, v132
	v_rcp_f32_e32 v133, v133
	v_rcp_f32_e32 v134, v134
	v_rcp_f32_e32 v135, v135
	v_cvt_pk_bf16_f32 v122, v132, v133
	v_cvt_pk_bf16_f32 v123, v134, v135
	s_nop 1
	v_permlane16_swap_b32_e32 v120, v122
	v_permlane16_swap_b32_e32 v121, v123
	global_store_dwordx4 v248, v[120:123], s[0:1]
	v_pk_mul_f32 v[132:133], v[108:109], v[250:251] op_sel_hi:[1,0]
	v_pk_mul_f32 v[134:135], v[110:111], v[250:251] op_sel_hi:[1,0]
	v_exp_f32_e32 v132, v132
	v_exp_f32_e32 v133, v133
	v_exp_f32_e32 v134, v134
	v_exp_f32_e32 v135, v135
	v_pk_add_f32 v[132:133], v[132:133], v[252:253] op_sel_hi:[1,0]
	v_pk_add_f32 v[134:135], v[134:135], v[252:253] op_sel_hi:[1,0]
	v_rcp_f32_e32 v132, v132
	v_rcp_f32_e32 v133, v133
	v_rcp_f32_e32 v134, v134
	v_rcp_f32_e32 v135, v135
	v_cvt_pk_bf16_f32 v108, v132, v133
	v_cvt_pk_bf16_f32 v109, v134, v135
	v_pk_mul_f32 v[132:133], v[100:101], v[250:251] op_sel_hi:[1,0]
	v_pk_mul_f32 v[134:135], v[102:103], v[250:251] op_sel_hi:[1,0]
	v_exp_f32_e32 v132, v132
	v_exp_f32_e32 v133, v133
	v_exp_f32_e32 v134, v134
	v_exp_f32_e32 v135, v135
	v_pk_add_f32 v[132:133], v[132:133], v[252:253] op_sel_hi:[1,0]
	v_pk_add_f32 v[134:135], v[134:135], v[252:253] op_sel_hi:[1,0]
	v_rcp_f32_e32 v132, v132
	v_rcp_f32_e32 v133, v133
	v_rcp_f32_e32 v134, v134
	v_rcp_f32_e32 v135, v135
	v_cvt_pk_bf16_f32 v110, v132, v133
	v_cvt_pk_bf16_f32 v111, v134, v135
	s_nop 1
	v_permlane16_swap_b32_e32 v108, v110
	v_permlane16_swap_b32_e32 v109, v111
	global_store_dwordx4 v247, v[108:111], s[0:1] offset:64
	v_pk_mul_f32 v[132:133], v[104:105], v[250:251] op_sel_hi:[1,0]
	v_pk_mul_f32 v[134:135], v[106:107], v[250:251] op_sel_hi:[1,0]
	v_exp_f32_e32 v132, v132
	v_exp_f32_e32 v133, v133
	v_exp_f32_e32 v134, v134
	v_exp_f32_e32 v135, v135
	v_pk_add_f32 v[132:133], v[132:133], v[252:253] op_sel_hi:[1,0]
	v_pk_add_f32 v[134:135], v[134:135], v[252:253] op_sel_hi:[1,0]
	v_rcp_f32_e32 v132, v132
	v_rcp_f32_e32 v133, v133
	v_rcp_f32_e32 v134, v134
	v_rcp_f32_e32 v135, v135
	v_cvt_pk_bf16_f32 v104, v132, v133
	v_cvt_pk_bf16_f32 v105, v134, v135
	v_pk_mul_f32 v[132:133], v[96:97], v[250:251] op_sel_hi:[1,0]
	v_pk_mul_f32 v[134:135], v[98:99], v[250:251] op_sel_hi:[1,0]
	v_exp_f32_e32 v132, v132
	v_exp_f32_e32 v133, v133
	v_exp_f32_e32 v134, v134
	v_exp_f32_e32 v135, v135
	v_pk_add_f32 v[132:133], v[132:133], v[252:253] op_sel_hi:[1,0]
	v_pk_add_f32 v[134:135], v[134:135], v[252:253] op_sel_hi:[1,0]
	v_rcp_f32_e32 v132, v132
	v_rcp_f32_e32 v133, v133
	v_rcp_f32_e32 v134, v134
	v_rcp_f32_e32 v135, v135
	v_cvt_pk_bf16_f32 v106, v132, v133
	v_cvt_pk_bf16_f32 v107, v134, v135
	s_nop 1
	v_permlane16_swap_b32_e32 v104, v106
	v_permlane16_swap_b32_e32 v105, v107
	global_store_dwordx4 v248, v[104:107], s[0:1] offset:64
	v_pk_mul_f32 v[132:133], v[92:93], v[250:251] op_sel_hi:[1,0]
	v_pk_mul_f32 v[134:135], v[94:95], v[250:251] op_sel_hi:[1,0]
	v_exp_f32_e32 v132, v132
	v_exp_f32_e32 v133, v133
	v_exp_f32_e32 v134, v134
; __device__ __forceinline__ float sigmoidf_(float x) { return __builtin_amdgcn_rcpf(1.f + __expf(-x)); }
; #define WIDE_STORE(BASE, LD, COFF, O) do { if ((m & 1) == 0) opend[n] = (O); \
;                 else *(uint4*)((BASE) + (size_t)tok * (LD) + (ncw - (COFF))) = swap_pair(opend[n], (O)); } while (0)
;     ...
;               f32x4 v = acc[ai][bj][m][n];
;               if (MODE == 0) {
;                 if (tn == 52) {
;                   if (ai == 0) *(float4*)((float*)(ws + OFF_DTR) + (size_t)tok * 128 + (nc - 13312)) = make_float4(v[0], v[1], v[2], v[3]);
;                 } else {
;                   u16* dst; int ld, c0;
;                   if (tn < 16) { dst = (u16*)(ws + OFF_Z); ld = 4096; c0 = 0; }
;                   else if (tn < 40) { dst = (u16*)(ws + OFF_RA); ld = 6144; c0 = 4096; }
;                   else if (tn < 48) { dst = (u16*)(ws + OFF_Q); ld = 2048; c0 = 10240; }
;                   else if (tn < 50) { dst = (u16*)(ws + OFF_K); ld = 512; c0 = 12288; }
;                   else { dst = (u16*)(ws + OFF_V); ld = 512; c0 = 12800; }
;                   uint2 o; o.x = pk2(v[0], v[1]); o.y = pk2(v[2], v[3]);
;                   WIDE_STORE(dst, ld, c0, o);
;                 }
;               } else if (MODE == 1) {
;                 uint2 o; o.x = pk2(sigmoidf_(v[0]), sigmoidf_(v[1])); o.y = pk2(sigmoidf_(v[2]), sigmoidf_(v[3]));
;                 WIDE_STORE((u16*)outp, 4096, 0, o);
	v_exp_f32_e32 v135, v135
	v_pk_add_f32 v[132:133], v[132:133], v[252:253] op_sel_hi:[1,0]
	v_pk_add_f32 v[134:135], v[134:135], v[252:253] op_sel_hi:[1,0]
	v_rcp_f32_e32 v132, v132
	v_rcp_f32_e32 v133, v133
	v_rcp_f32_e32 v134, v134
	v_rcp_f32_e32 v135, v135
	v_cvt_pk_bf16_f32 v92, v132, v133
	v_cvt_pk_bf16_f32 v93, v134, v135
	v_pk_mul_f32 v[132:133], v[84:85], v[250:251] op_sel_hi:[1,0]
	v_pk_mul_f32 v[134:135], v[86:87], v[250:251] op_sel_hi:[1,0]
	v_exp_f32_e32 v132, v132
	v_exp_f32_e32 v133, v133
	v_exp_f32_e32 v134, v134
	v_exp_f32_e32 v135, v135
	v_pk_add_f32 v[132:133], v[132:133], v[252:253] op_sel_hi:[1,0]
	v_pk_add_f32 v[134:135], v[134:135], v[252:253] op_sel_hi:[1,0]
	v_rcp_f32_e32 v132, v132
	v_rcp_f32_e32 v133, v133
	v_rcp_f32_e32 v134, v134
	v_rcp_f32_e32 v135, v135
	v_cvt_pk_bf16_f32 v94, v132, v133
	v_cvt_pk_bf16_f32 v95, v134, v135
	s_nop 1
	v_permlane16_swap_b32_e32 v92, v94
	v_permlane16_swap_b32_e32 v93, v95
	global_store_dwordx4 v249, v[92:95], s[0:1]
	v_pk_mul_f32 v[132:133], v[88:89], v[250:251] op_sel_hi:[1,0]
	v_pk_mul_f32 v[134:135], v[90:91], v[250:251] op_sel_hi:[1,0]
	v_exp_f32_e32 v132, v132
	v_exp_f32_e32 v133, v133
	v_exp_f32_e32 v134, v134
	v_exp_f32_e32 v135, v135
	v_pk_add_f32 v[132:133], v[132:133], v[252:253] op_sel_hi:[1,0]
	v_pk_add_f32 v[134:135], v[134:135], v[252:253] op_sel_hi:[1,0]
	v_rcp_f32_e32 v132, v132
	v_rcp_f32_e32 v133, v133
	v_rcp_f32_e32 v134, v134
	v_rcp_f32_e32 v135, v135
	v_cvt_pk_bf16_f32 v88, v132, v133
	v_cvt_pk_bf16_f32 v89, v134, v135
	v_pk_mul_f32 v[132:133], v[80:81], v[250:251] op_sel_hi:[1,0]
	v_pk_mul_f32 v[134:135], v[82:83], v[250:251] op_sel_hi:[1,0]
	v_exp_f32_e32 v132, v132
	v_exp_f32_e32 v133, v133
	v_exp_f32_e32 v134, v134
	v_exp_f32_e32 v135, v135
	v_pk_add_f32 v[132:133], v[132:133], v[252:253] op_sel_hi:[1,0]
	v_pk_add_f32 v[134:135], v[134:135], v[252:253] op_sel_hi:[1,0]
	v_rcp_f32_e32 v132, v132
	v_rcp_f32_e32 v133, v133
	v_rcp_f32_e32 v134, v134
	v_rcp_f32_e32 v135, v135
	v_cvt_pk_bf16_f32 v90, v132, v133
	v_cvt_pk_bf16_f32 v91, v134, v135
	s_nop 1
	v_permlane16_swap_b32_e32 v88, v90
	v_permlane16_swap_b32_e32 v89, v91
	global_store_dwordx4 v254, v[88:91], s[0:1]
	v_pk_mul_f32 v[132:133], v[76:77], v[250:251] op_sel_hi:[1,0]
	v_pk_mul_f32 v[134:135], v[78:79], v[250:251] op_sel_hi:[1,0]
	v_exp_f32_e32 v132, v132
	v_exp_f32_e32 v133, v133
	v_exp_f32_e32 v134, v134
	v_exp_f32_e32 v135, v135
	v_pk_add_f32 v[132:133], v[132:133], v[252:253] op_sel_hi:[1,0]
	v_pk_add_f32 v[134:135], v[134:135], v[252:253] op_sel_hi:[1,0]
	v_rcp_f32_e32 v132, v132
	v_rcp_f32_e32 v133, v133
	v_rcp_f32_e32 v134, v134
	v_rcp_f32_e32 v135, v135
	v_cvt_pk_bf16_f32 v76, v132, v133
	v_cvt_pk_bf16_f32 v77, v134, v135
	v_pk_mul_f32 v[132:133], v[68:69], v[250:251] op_sel_hi:[1,0]
	v_pk_mul_f32 v[134:135], v[70:71], v[250:251] op_sel_hi:[1,0]
	v_exp_f32_e32 v132, v132
	v_exp_f32_e32 v133, v133
	v_exp_f32_e32 v134, v134
	v_exp_f32_e32 v135, v135
	v_pk_add_f32 v[132:133], v[132:133], v[252:253] op_sel_hi:[1,0]
	v_pk_add_f32 v[134:135], v[134:135], v[252:253] op_sel_hi:[1,0]
	v_rcp_f32_e32 v132, v132
	v_rcp_f32_e32 v133, v133
	v_rcp_f32_e32 v134, v134
	v_rcp_f32_e32 v135, v135
	v_cvt_pk_bf16_f32 v78, v132, v133
	v_cvt_pk_bf16_f32 v79, v134, v135
	s_nop 1
	v_permlane16_swap_b32_e32 v76, v78
	v_permlane16_swap_b32_e32 v77, v79
	global_store_dwordx4 v249, v[76:79], s[0:1] offset:64
	v_pk_mul_f32 v[132:133], v[72:73], v[250:251] op_sel_hi:[1,0]
	v_pk_mul_f32 v[134:135], v[74:75], v[250:251] op_sel_hi:[1,0]
	v_exp_f32_e32 v132, v132
	v_exp_f32_e32 v133, v133
	v_exp_f32_e32 v134, v134
	v_exp_f32_e32 v135, v135
	v_pk_add_f32 v[132:133], v[132:133], v[252:253] op_sel_hi:[1,0]
	v_pk_add_f32 v[134:135], v[134:135], v[252:253] op_sel_hi:[1,0]
	v_rcp_f32_e32 v132, v132
	v_rcp_f32_e32 v133, v133
	v_rcp_f32_e32 v134, v134
	v_rcp_f32_e32 v135, v135
	v_cvt_pk_bf16_f32 v72, v132, v133
	v_cvt_pk_bf16_f32 v73, v134, v135
	v_pk_mul_f32 v[132:133], v[64:65], v[250:251] op_sel_hi:[1,0]
	v_pk_mul_f32 v[134:135], v[66:67], v[250:251] op_sel_hi:[1,0]
	v_exp_f32_e32 v132, v132
	v_exp_f32_e32 v133, v133
	v_exp_f32_e32 v134, v134
	v_exp_f32_e32 v135, v135
	v_pk_add_f32 v[132:133], v[132:133], v[252:253] op_sel_hi:[1,0]
	v_pk_add_f32 v[134:135], v[134:135], v[252:253] op_sel_hi:[1,0]
	v_rcp_f32_e32 v132, v132
	v_rcp_f32_e32 v133, v133
	v_rcp_f32_e32 v134, v134
	v_rcp_f32_e32 v135, v135
	v_cvt_pk_bf16_f32 v74, v132, v133
	v_cvt_pk_bf16_f32 v75, v134, v135
	s_nop 1
	v_permlane16_swap_b32_e32 v72, v74
	v_permlane16_swap_b32_e32 v73, v75
	global_store_dwordx4 v254, v[72:75], s[0:1] offset:64
	v_pk_mul_f32 v[132:133], v[60:61], v[250:251] op_sel_hi:[1,0]
	v_pk_mul_f32 v[134:135], v[62:63], v[250:251] op_sel_hi:[1,0]
	v_exp_f32_e32 v132, v132
	v_exp_f32_e32 v133, v133
	v_exp_f32_e32 v134, v134
	v_exp_f32_e32 v135, v135
	v_pk_add_f32 v[132:133], v[132:133], v[252:253] op_sel_hi:[1,0]
	v_pk_add_f32 v[134:135], v[134:135], v[252:253] op_sel_hi:[1,0]
	v_rcp_f32_e32 v132, v132
	v_rcp_f32_e32 v133, v133
	v_rcp_f32_e32 v134, v134
	v_rcp_f32_e32 v135, v135
	v_cvt_pk_bf16_f32 v60, v132, v133
	v_cvt_pk_bf16_f32 v61, v134, v135
	v_pk_mul_f32 v[132:133], v[52:53], v[250:251] op_sel_hi:[1,0]
	v_pk_mul_f32 v[134:135], v[54:55], v[250:251] op_sel_hi:[1,0]
	v_exp_f32_e32 v132, v132
	v_exp_f32_e32 v133, v133
	v_exp_f32_e32 v134, v134
	v_exp_f32_e32 v135, v135
	v_pk_add_f32 v[132:133], v[132:133], v[252:253] op_sel_hi:[1,0]
	v_pk_add_f32 v[134:135], v[134:135], v[252:253] op_sel_hi:[1,0]
	v_rcp_f32_e32 v132, v132
	v_rcp_f32_e32 v133, v133
	v_rcp_f32_e32 v134, v134
	v_rcp_f32_e32 v135, v135
	v_cvt_pk_bf16_f32 v62, v132, v133
; __device__ __forceinline__ float sigmoidf_(float x) { return __builtin_amdgcn_rcpf(1.f + __expf(-x)); }
; #define WIDE_STORE(BASE, LD, COFF, O) do { if ((m & 1) == 0) opend[n] = (O); \
;                 else *(uint4*)((BASE) + (size_t)tok * (LD) + (ncw - (COFF))) = swap_pair(opend[n], (O)); } while (0)
;     ...
;               f32x4 v = acc[ai][bj][m][n];
;               if (MODE == 0) {
;                 if (tn == 52) {
;                   if (ai == 0) *(float4*)((float*)(ws + OFF_DTR) + (size_t)tok * 128 + (nc - 13312)) = make_float4(v[0], v[1], v[2], v[3]);
;                 } else {
;                   u16* dst; int ld, c0;
;                   if (tn < 16) { dst = (u16*)(ws + OFF_Z); ld = 4096; c0 = 0; }
;                   else if (tn < 40) { dst = (u16*)(ws + OFF_RA); ld = 6144; c0 = 4096; }
;                   else if (tn < 48) { dst = (u16*)(ws + OFF_Q); ld = 2048; c0 = 10240; }
;                   else if (tn < 50) { dst = (u16*)(ws + OFF_K); ld = 512; c0 = 12288; }
;                   else { dst = (u16*)(ws + OFF_V); ld = 512; c0 = 12800; }
;                   uint2 o; o.x = pk2(v[0], v[1]); o.y = pk2(v[2], v[3]);
;                   WIDE_STORE(dst, ld, c0, o);
;                 }
;               } else if (MODE == 1) {
;                 uint2 o; o.x = pk2(sigmoidf_(v[0]), sigmoidf_(v[1])); o.y = pk2(sigmoidf_(v[2]), sigmoidf_(v[3]));
;                 WIDE_STORE((u16*)outp, 4096, 0, o);
	v_cvt_pk_bf16_f32 v63, v134, v135
	s_nop 1
	v_permlane16_swap_b32_e32 v60, v62
	v_permlane16_swap_b32_e32 v61, v63
	global_store_dwordx4 v247, v[60:63], s[0:1] offset:256
	v_pk_mul_f32 v[132:133], v[56:57], v[250:251] op_sel_hi:[1,0]
	v_pk_mul_f32 v[134:135], v[58:59], v[250:251] op_sel_hi:[1,0]
	v_exp_f32_e32 v132, v132
	v_exp_f32_e32 v133, v133
	v_exp_f32_e32 v134, v134
	v_exp_f32_e32 v135, v135
	v_pk_add_f32 v[132:133], v[132:133], v[252:253] op_sel_hi:[1,0]
	v_pk_add_f32 v[134:135], v[134:135], v[252:253] op_sel_hi:[1,0]
	v_rcp_f32_e32 v132, v132
	v_rcp_f32_e32 v133, v133
	v_rcp_f32_e32 v134, v134
	v_rcp_f32_e32 v135, v135
	v_cvt_pk_bf16_f32 v56, v132, v133
	v_cvt_pk_bf16_f32 v57, v134, v135
	v_pk_mul_f32 v[132:133], v[48:49], v[250:251] op_sel_hi:[1,0]
	v_pk_mul_f32 v[134:135], v[50:51], v[250:251] op_sel_hi:[1,0]
	v_exp_f32_e32 v132, v132
	v_exp_f32_e32 v133, v133
	v_exp_f32_e32 v134, v134
	v_exp_f32_e32 v135, v135
	v_pk_add_f32 v[132:133], v[132:133], v[252:253] op_sel_hi:[1,0]
	v_pk_add_f32 v[134:135], v[134:135], v[252:253] op_sel_hi:[1,0]
	v_rcp_f32_e32 v132, v132
	v_rcp_f32_e32 v133, v133
	v_rcp_f32_e32 v134, v134
	v_rcp_f32_e32 v135, v135
	v_cvt_pk_bf16_f32 v58, v132, v133
	v_cvt_pk_bf16_f32 v59, v134, v135
	s_nop 1
	v_permlane16_swap_b32_e32 v56, v58
	v_permlane16_swap_b32_e32 v57, v59
	global_store_dwordx4 v248, v[56:59], s[0:1] offset:256
	v_pk_mul_f32 v[132:133], v[44:45], v[250:251] op_sel_hi:[1,0]
	v_pk_mul_f32 v[134:135], v[46:47], v[250:251] op_sel_hi:[1,0]
	v_exp_f32_e32 v132, v132
	v_exp_f32_e32 v133, v133
	v_exp_f32_e32 v134, v134
	v_exp_f32_e32 v135, v135
	v_pk_add_f32 v[132:133], v[132:133], v[252:253] op_sel_hi:[1,0]
	v_pk_add_f32 v[134:135], v[134:135], v[252:253] op_sel_hi:[1,0]
	v_rcp_f32_e32 v132, v132
	v_rcp_f32_e32 v133, v133
	v_rcp_f32_e32 v134, v134
	v_rcp_f32_e32 v135, v135
	v_cvt_pk_bf16_f32 v44, v132, v133
	v_cvt_pk_bf16_f32 v45, v134, v135
	v_pk_mul_f32 v[132:133], v[36:37], v[250:251] op_sel_hi:[1,0]
	v_pk_mul_f32 v[134:135], v[38:39], v[250:251] op_sel_hi:[1,0]
	v_exp_f32_e32 v132, v132
	v_exp_f32_e32 v133, v133
	v_exp_f32_e32 v134, v134
	v_exp_f32_e32 v135, v135
	v_pk_add_f32 v[132:133], v[132:133], v[252:253] op_sel_hi:[1,0]
	v_pk_add_f32 v[134:135], v[134:135], v[252:253] op_sel_hi:[1,0]
	v_rcp_f32_e32 v132, v132
	v_rcp_f32_e32 v133, v133
	v_rcp_f32_e32 v134, v134
	v_rcp_f32_e32 v135, v135
	v_cvt_pk_bf16_f32 v46, v132, v133
	v_cvt_pk_bf16_f32 v47, v134, v135
	s_nop 1
	v_permlane16_swap_b32_e32 v44, v46
	v_permlane16_swap_b32_e32 v45, v47
	global_store_dwordx4 v247, v[44:47], s[0:1] offset:320
	v_pk_mul_f32 v[132:133], v[40:41], v[250:251] op_sel_hi:[1,0]
	v_pk_mul_f32 v[134:135], v[42:43], v[250:251] op_sel_hi:[1,0]
	v_exp_f32_e32 v132, v132
	v_exp_f32_e32 v133, v133
	v_exp_f32_e32 v134, v134
	v_exp_f32_e32 v135, v135
	v_pk_add_f32 v[132:133], v[132:133], v[252:253] op_sel_hi:[1,0]
	v_pk_add_f32 v[134:135], v[134:135], v[252:253] op_sel_hi:[1,0]
	v_rcp_f32_e32 v132, v132
	v_rcp_f32_e32 v133, v133
	v_rcp_f32_e32 v134, v134
	v_rcp_f32_e32 v135, v135
	v_cvt_pk_bf16_f32 v40, v132, v133
	v_cvt_pk_bf16_f32 v41, v134, v135
	v_pk_mul_f32 v[132:133], v[32:33], v[250:251] op_sel_hi:[1,0]
	v_pk_mul_f32 v[134:135], v[34:35], v[250:251] op_sel_hi:[1,0]
	v_exp_f32_e32 v132, v132
	v_exp_f32_e32 v133, v133
	v_exp_f32_e32 v134, v134
	v_exp_f32_e32 v135, v135
	v_pk_add_f32 v[132:133], v[132:133], v[252:253] op_sel_hi:[1,0]
	v_pk_add_f32 v[134:135], v[134:135], v[252:253] op_sel_hi:[1,0]
	v_rcp_f32_e32 v132, v132
	v_rcp_f32_e32 v133, v133
	v_rcp_f32_e32 v134, v134
	v_rcp_f32_e32 v135, v135
	v_cvt_pk_bf16_f32 v42, v132, v133
	v_cvt_pk_bf16_f32 v43, v134, v135
	s_nop 1
	v_permlane16_swap_b32_e32 v40, v42
	v_permlane16_swap_b32_e32 v41, v43
	global_store_dwordx4 v248, v[40:43], s[0:1] offset:320
	v_pk_mul_f32 v[132:133], v[28:29], v[250:251] op_sel_hi:[1,0]
	v_pk_mul_f32 v[134:135], v[30:31], v[250:251] op_sel_hi:[1,0]
	v_exp_f32_e32 v132, v132
	v_exp_f32_e32 v133, v133
	v_exp_f32_e32 v134, v134
	v_exp_f32_e32 v135, v135
	v_pk_add_f32 v[132:133], v[132:133], v[252:253] op_sel_hi:[1,0]
	v_pk_add_f32 v[134:135], v[134:135], v[252:253] op_sel_hi:[1,0]
	v_rcp_f32_e32 v132, v132
	v_rcp_f32_e32 v133, v133
	v_rcp_f32_e32 v134, v134
	v_rcp_f32_e32 v135, v135
	v_cvt_pk_bf16_f32 v28, v132, v133
	v_cvt_pk_bf16_f32 v29, v134, v135
; __device__ __forceinline__ float sigmoidf_(float x) { return __builtin_amdgcn_rcpf(1.f + __expf(-x)); }
; #define WIDE_STORE(BASE, LD, COFF, O) do { if ((m & 1) == 0) opend[n] = (O); \
;                 else *(uint4*)((BASE) + (size_t)tok * (LD) + (ncw - (COFF))) = swap_pair(opend[n], (O)); } while (0)
;     ...
;               f32x4 v = acc[ai][bj][m][n];
;               if (MODE == 0) {
;                 if (tn == 52) {
;                   if (ai == 0) *(float4*)((float*)(ws + OFF_DTR) + (size_t)tok * 128 + (nc - 13312)) = make_float4(v[0], v[1], v[2], v[3]);
;                 } else {
;                   u16* dst; int ld, c0;
;                   if (tn < 16) { dst = (u16*)(ws + OFF_Z); ld = 4096; c0 = 0; }
;                   else if (tn < 40) { dst = (u16*)(ws + OFF_RA); ld = 6144; c0 = 4096; }
;                   else if (tn < 48) { dst = (u16*)(ws + OFF_Q); ld = 2048; c0 = 10240; }
;                   else if (tn < 50) { dst = (u16*)(ws + OFF_K); ld = 512; c0 = 12288; }
;                   else { dst = (u16*)(ws + OFF_V); ld = 512; c0 = 12800; }
;                   uint2 o; o.x = pk2(v[0], v[1]); o.y = pk2(v[2], v[3]);
;                   WIDE_STORE(dst, ld, c0, o);
;                 }
;               } else if (MODE == 1) {
;                 uint2 o; o.x = pk2(sigmoidf_(v[0]), sigmoidf_(v[1])); o.y = pk2(sigmoidf_(v[2]), sigmoidf_(v[3]));
;                 WIDE_STORE((u16*)outp, 4096, 0, o);
;     ...
;     asm volatile("s_waitcnt vmcnt(0)" ::: "memory");
;     if (has_next && wr == 1) __builtin_amdgcn_s_barrier();
	v_pk_mul_f32 v[132:133], v[20:21], v[250:251] op_sel_hi:[1,0]
	v_pk_mul_f32 v[134:135], v[22:23], v[250:251] op_sel_hi:[1,0]
	v_exp_f32_e32 v132, v132
	v_exp_f32_e32 v133, v133
	v_exp_f32_e32 v134, v134
	v_exp_f32_e32 v135, v135
	v_pk_add_f32 v[132:133], v[132:133], v[252:253] op_sel_hi:[1,0]
	v_pk_add_f32 v[134:135], v[134:135], v[252:253] op_sel_hi:[1,0]
	v_rcp_f32_e32 v132, v132
	v_rcp_f32_e32 v133, v133
	v_rcp_f32_e32 v134, v134
	v_rcp_f32_e32 v135, v135
	v_cvt_pk_bf16_f32 v30, v132, v133
	v_cvt_pk_bf16_f32 v31, v134, v135
	s_nop 1
	v_permlane16_swap_b32_e32 v28, v30
	v_permlane16_swap_b32_e32 v29, v31
	global_store_dwordx4 v249, v[28:31], s[0:1] offset:256
	v_pk_mul_f32 v[132:133], v[24:25], v[250:251] op_sel_hi:[1,0]
	v_pk_mul_f32 v[134:135], v[26:27], v[250:251] op_sel_hi:[1,0]
	v_exp_f32_e32 v132, v132
	v_exp_f32_e32 v133, v133
	v_exp_f32_e32 v134, v134
	v_exp_f32_e32 v135, v135
	v_pk_add_f32 v[132:133], v[132:133], v[252:253] op_sel_hi:[1,0]
	v_pk_add_f32 v[134:135], v[134:135], v[252:253] op_sel_hi:[1,0]
	v_rcp_f32_e32 v132, v132
	v_rcp_f32_e32 v133, v133
	v_rcp_f32_e32 v134, v134
	v_rcp_f32_e32 v135, v135
	v_cvt_pk_bf16_f32 v24, v132, v133
	v_cvt_pk_bf16_f32 v25, v134, v135
	v_pk_mul_f32 v[132:133], v[16:17], v[250:251] op_sel_hi:[1,0]
	v_pk_mul_f32 v[134:135], v[18:19], v[250:251] op_sel_hi:[1,0]
	v_exp_f32_e32 v132, v132
	v_exp_f32_e32 v133, v133
	v_exp_f32_e32 v134, v134
	v_exp_f32_e32 v135, v135
	v_pk_add_f32 v[132:133], v[132:133], v[252:253] op_sel_hi:[1,0]
	v_pk_add_f32 v[134:135], v[134:135], v[252:253] op_sel_hi:[1,0]
	v_rcp_f32_e32 v132, v132
	v_rcp_f32_e32 v133, v133
	v_rcp_f32_e32 v134, v134
	v_rcp_f32_e32 v135, v135
	v_cvt_pk_bf16_f32 v26, v132, v133
	v_cvt_pk_bf16_f32 v27, v134, v135
	s_nop 1
	v_permlane16_swap_b32_e32 v24, v26
	v_permlane16_swap_b32_e32 v25, v27
	global_store_dwordx4 v254, v[24:27], s[0:1] offset:256
	v_pk_mul_f32 v[132:133], v[12:13], v[250:251] op_sel_hi:[1,0]
	v_pk_mul_f32 v[134:135], v[14:15], v[250:251] op_sel_hi:[1,0]
	v_exp_f32_e32 v132, v132
	v_exp_f32_e32 v133, v133
	v_exp_f32_e32 v134, v134
	v_exp_f32_e32 v135, v135
	v_pk_add_f32 v[132:133], v[132:133], v[252:253] op_sel_hi:[1,0]
	v_pk_add_f32 v[134:135], v[134:135], v[252:253] op_sel_hi:[1,0]
	v_rcp_f32_e32 v132, v132
	v_rcp_f32_e32 v133, v133
	v_rcp_f32_e32 v134, v134
	v_rcp_f32_e32 v135, v135
	v_cvt_pk_bf16_f32 v12, v132, v133
	v_cvt_pk_bf16_f32 v13, v134, v135
	v_pk_mul_f32 v[132:133], v[4:5], v[250:251] op_sel_hi:[1,0]
	v_pk_mul_f32 v[134:135], v[6:7], v[250:251] op_sel_hi:[1,0]
	v_exp_f32_e32 v132, v132
	v_exp_f32_e32 v133, v133
	v_exp_f32_e32 v134, v134
	v_exp_f32_e32 v135, v135
	v_pk_add_f32 v[132:133], v[132:133], v[252:253] op_sel_hi:[1,0]
	v_pk_add_f32 v[134:135], v[134:135], v[252:253] op_sel_hi:[1,0]
	v_rcp_f32_e32 v132, v132
	v_rcp_f32_e32 v133, v133
	v_rcp_f32_e32 v134, v134
	v_rcp_f32_e32 v135, v135
	v_cvt_pk_bf16_f32 v14, v132, v133
	v_cvt_pk_bf16_f32 v15, v134, v135
	s_nop 1
	v_permlane16_swap_b32_e32 v12, v14
	v_permlane16_swap_b32_e32 v13, v15
	global_store_dwordx4 v249, v[12:15], s[0:1] offset:320
	v_pk_mul_f32 v[132:133], v[8:9], v[250:251] op_sel_hi:[1,0]
	v_pk_mul_f32 v[134:135], v[10:11], v[250:251] op_sel_hi:[1,0]
	v_exp_f32_e32 v132, v132
	v_exp_f32_e32 v133, v133
	v_exp_f32_e32 v134, v134
	v_exp_f32_e32 v135, v135
	v_pk_add_f32 v[132:133], v[132:133], v[252:253] op_sel_hi:[1,0]
	v_pk_add_f32 v[134:135], v[134:135], v[252:253] op_sel_hi:[1,0]
	v_rcp_f32_e32 v132, v132
	v_rcp_f32_e32 v133, v133
	v_rcp_f32_e32 v134, v134
	v_rcp_f32_e32 v135, v135
	v_cvt_pk_bf16_f32 v8, v132, v133
	v_cvt_pk_bf16_f32 v9, v134, v135
	v_pk_mul_f32 v[132:133], v[0:1], v[250:251] op_sel_hi:[1,0]
	v_pk_mul_f32 v[134:135], v[2:3], v[250:251] op_sel_hi:[1,0]
	v_exp_f32_e32 v132, v132
	v_exp_f32_e32 v133, v133
	v_exp_f32_e32 v134, v134
	v_exp_f32_e32 v135, v135
	v_pk_add_f32 v[132:133], v[132:133], v[252:253] op_sel_hi:[1,0]
	v_pk_add_f32 v[134:135], v[134:135], v[252:253] op_sel_hi:[1,0]
	v_rcp_f32_e32 v132, v132
	v_rcp_f32_e32 v133, v133
	v_rcp_f32_e32 v134, v134
	v_rcp_f32_e32 v135, v135
	v_cvt_pk_bf16_f32 v10, v132, v133
	v_cvt_pk_bf16_f32 v11, v134, v135
	s_nop 1
	v_permlane16_swap_b32_e32 v8, v10
	v_permlane16_swap_b32_e32 v9, v11
	global_store_dwordx4 v254, v[8:11], s[0:1] offset:320
	s_waitcnt vmcnt(0)
	s_waitcnt vmcnt(0) lgkmcnt(0)
	s_barrier
	s_mov_b64 s[0:1], 0
